# plus FNet weight fold inner loop: 16 LDS reads in flight refilled in place instead of read-wait-use one at a time (same accumulation order)
# speedup vs baseline: 1.0286x; 1.0085x over previous
; #define LAS __attribute__((address_space(3)))
; __device__ __forceinline__ void phase_prep(const Params& p, LAS unsigned char* lds) {
;     ...
;             for (int kci = 0; kci < 4; ++kci) { const int kc = kc4 * 4 + kci; asm volatile("" ::: "memory");
;             const int k = kc * 128 + (tid & 127), eg = tid >> 7;
;             const float* row = p.w_in + ((size_t)l * DM + k) * INW + ZW + g * 64;
;             float a[16];
; #pragma unroll
;             for (int j = 0; j < 16; ++j) a[j] = 0.f;
;             f32x4 rw[16];
; #pragma unroll
;             for (int c4 = 0; c4 < 16; ++c4) rw[c4] = *(const f32x4*)(row + 4 * c4);
; #pragma unroll
;             for (int c4 = 0; c4 < 16; ++c4)
; #pragma unroll
;                 for (int cc = 0; cc < 4; ++cc) { const float wv = rw[c4][cc]; const LAS f32x4* mp = (const LAS f32x4*)(Mf + (4 * c4 + cc) * 64 + eg * 16);
; #pragma unroll
;                     for (int j4 = 0; j4 < 4; ++j4) { const f32x4 mv = mp[j4]; a[4 * j4 + 0] += wv * mv[0]; a[4 * j4 + 1] += wv * mv[1]; a[4 * j4 + 2] += wv * mv[2]; a[4 * j4 + 3] += wv * mv[3]; } }
.LBB0_581:
	global_load_dwordx4 v[48:51], v[62:63], off offset:-80
	global_load_dwordx4 v[52:55], v[62:63], off offset:-96
	global_load_dwordx4 v[86:89], v[62:63], off offset:-112
	global_load_dwordx4 v[90:93], v[62:63], off offset:-128
	global_load_dwordx4 v[32:35], v[62:63], off offset:-16
	global_load_dwordx4 v[36:39], v[62:63], off offset:-32
	global_load_dwordx4 v[40:43], v[62:63], off offset:-48
	global_load_dwordx4 v[44:47], v[62:63], off offset:-64
	global_load_dwordx4 v[16:19], v[62:63], off offset:48
	global_load_dwordx4 v[20:23], v[62:63], off offset:32
	global_load_dwordx4 v[24:27], v[62:63], off offset:16
	global_load_dwordx4 v[28:31], v[62:63], off
	global_load_dwordx4 v[0:3], v[62:63], off offset:112
	global_load_dwordx4 v[4:7], v[62:63], off offset:96
	global_load_dwordx4 v[8:11], v[62:63], off offset:80
	global_load_dwordx4 v[12:15], v[62:63], off offset:64
	s_mov_b32 s2, 0x4001000
	ds_read_b128 v[102:105], v66 offset:1024
	ds_read_b128 v[106:109], v66 offset:1040
	ds_read_b128 v[110:113], v66 offset:1056
	ds_read_b128 v[114:117], v66 offset:1072
	ds_read_b128 v[118:121], v66 offset:1280
	ds_read_b128 v[122:125], v66 offset:1296
	ds_read_b128 v[126:129], v66 offset:1312
	ds_read_b128 v[130:133], v66 offset:1328
	ds_read_b128 v[134:137], v66 offset:1536
	ds_read_b128 v[138:141], v66 offset:1552
	ds_read_b128 v[142:145], v66 offset:1568
	ds_read_b128 v[146:149], v66 offset:1584
	ds_read_b128 v[150:153], v66 offset:1792
	ds_read_b128 v[158:161], v66 offset:1808
	ds_read_b128 v[162:165], v66 offset:1824
	ds_read_b128 v[166:169], v66 offset:1840
	s_waitcnt vmcnt(0)
	s_waitcnt lgkmcnt(15)
	v_mul_f32_e32 v84, v90, v102
	v_mul_f32_e32 v83, v90, v103
	v_mul_f32_e32 v82, v90, v104
	v_mul_f32_e32 v81, v90, v105
	ds_read_b128 v[102:105], v66 offset:2048
	s_waitcnt lgkmcnt(15)
	v_mul_f32_e32 v80, v90, v106
	v_mul_f32_e32 v79, v90, v107
	v_mul_f32_e32 v78, v90, v108
	v_mul_f32_e32 v77, v90, v109
	ds_read_b128 v[106:109], v66 offset:2064
	s_waitcnt lgkmcnt(15)
	v_mul_f32_e32 v76, v90, v110
	v_mul_f32_e32 v75, v90, v111
	v_mul_f32_e32 v74, v90, v112
	v_mul_f32_e32 v73, v90, v113
	ds_read_b128 v[110:113], v66 offset:2080
	s_waitcnt lgkmcnt(15)
	v_mul_f32_e32 v72, v90, v114
	v_mul_f32_e32 v71, v90, v115
	v_mul_f32_e32 v70, v90, v116
	v_mul_f32_e32 v69, v90, v117
	ds_read_b128 v[114:117], v66 offset:2096
	s_waitcnt lgkmcnt(15)
	v_fmac_f32_e32 v84, v91, v118
	v_fmac_f32_e32 v83, v91, v119
	v_fmac_f32_e32 v82, v91, v120
	v_fmac_f32_e32 v81, v91, v121
	ds_read_b128 v[118:121], v66 offset:2304
	s_waitcnt lgkmcnt(15)
	v_fmac_f32_e32 v80, v91, v122
	v_fmac_f32_e32 v79, v91, v123
	v_fmac_f32_e32 v78, v91, v124
	v_fmac_f32_e32 v77, v91, v125
	ds_read_b128 v[122:125], v66 offset:2320
	s_waitcnt lgkmcnt(15)
	v_fmac_f32_e32 v76, v91, v126
	v_fmac_f32_e32 v75, v91, v127
	v_fmac_f32_e32 v74, v91, v128
	v_fmac_f32_e32 v73, v91, v129
	ds_read_b128 v[126:129], v66 offset:2336
	s_waitcnt lgkmcnt(15)
	v_fmac_f32_e32 v72, v91, v130
	v_fmac_f32_e32 v71, v91, v131
	v_fmac_f32_e32 v70, v91, v132
	v_fmac_f32_e32 v69, v91, v133
	ds_read_b128 v[130:133], v66 offset:2352
	s_waitcnt lgkmcnt(15)
	v_fmac_f32_e32 v84, v92, v134
	v_fmac_f32_e32 v83, v92, v135
	v_fmac_f32_e32 v82, v92, v136
	v_fmac_f32_e32 v81, v92, v137
	ds_read_b128 v[134:137], v66 offset:2560
	s_waitcnt lgkmcnt(15)
	v_fmac_f32_e32 v80, v92, v138
	v_fmac_f32_e32 v79, v92, v139
	v_fmac_f32_e32 v78, v92, v140
	v_fmac_f32_e32 v77, v92, v141
	ds_read_b128 v[138:141], v66 offset:2576
	s_waitcnt lgkmcnt(15)
	v_fmac_f32_e32 v76, v92, v142
	v_fmac_f32_e32 v75, v92, v143
	v_fmac_f32_e32 v74, v92, v144
	v_fmac_f32_e32 v73, v92, v145
	ds_read_b128 v[142:145], v66 offset:2592
	s_waitcnt lgkmcnt(15)
	v_fmac_f32_e32 v72, v92, v146
	v_fmac_f32_e32 v71, v92, v147
	v_fmac_f32_e32 v70, v92, v148
	v_fmac_f32_e32 v69, v92, v149
	ds_read_b128 v[146:149], v66 offset:2608
	s_waitcnt lgkmcnt(15)
	v_fmac_f32_e32 v84, v93, v150
	v_fmac_f32_e32 v83, v93, v151
	v_fmac_f32_e32 v82, v93, v152
	v_fmac_f32_e32 v81, v93, v153
	ds_read_b128 v[150:153], v66 offset:2816
	s_waitcnt lgkmcnt(15)
	v_fmac_f32_e32 v80, v93, v158
	v_fmac_f32_e32 v79, v93, v159
	v_fmac_f32_e32 v78, v93, v160
	v_fmac_f32_e32 v77, v93, v161
	ds_read_b128 v[158:161], v66 offset:2832
	s_waitcnt lgkmcnt(15)
	v_fmac_f32_e32 v76, v93, v162
	v_fmac_f32_e32 v75, v93, v163
	v_fmac_f32_e32 v74, v93, v164
	v_fmac_f32_e32 v73, v93, v165
	ds_read_b128 v[162:165], v66 offset:2848
	s_waitcnt lgkmcnt(15)
	v_fmac_f32_e32 v72, v93, v166
	v_fmac_f32_e32 v71, v93, v167
	v_fmac_f32_e32 v70, v93, v168
	v_fmac_f32_e32 v69, v93, v169
	ds_read_b128 v[166:169], v66 offset:2864
	s_waitcnt lgkmcnt(15)
	v_fmac_f32_e32 v84, v86, v102
	v_fmac_f32_e32 v83, v86, v103
	v_fmac_f32_e32 v82, v86, v104
	v_fmac_f32_e32 v81, v86, v105
	ds_read_b128 v[102:105], v66 offset:3072
	s_waitcnt lgkmcnt(15)
	v_fmac_f32_e32 v80, v86, v106
	v_fmac_f32_e32 v79, v86, v107
	v_fmac_f32_e32 v78, v86, v108
	v_fmac_f32_e32 v77, v86, v109
	ds_read_b128 v[106:109], v66 offset:3088
	s_waitcnt lgkmcnt(15)
	v_fmac_f32_e32 v76, v86, v110
	v_fmac_f32_e32 v75, v86, v111
	v_fmac_f32_e32 v74, v86, v112
	v_fmac_f32_e32 v73, v86, v113
	ds_read_b128 v[110:113], v66 offset:3104
	s_waitcnt lgkmcnt(15)
	v_fmac_f32_e32 v72, v86, v114
	v_fmac_f32_e32 v71, v86, v115
	v_fmac_f32_e32 v70, v86, v116
	v_fmac_f32_e32 v69, v86, v117
	ds_read_b128 v[114:117], v66 offset:3120
	s_waitcnt lgkmcnt(15)
	v_fmac_f32_e32 v84, v87, v118
	v_fmac_f32_e32 v83, v87, v119
	v_fmac_f32_e32 v82, v87, v120
	v_fmac_f32_e32 v81, v87, v121
	ds_read_b128 v[118:121], v66 offset:3328
	s_waitcnt lgkmcnt(15)
; #define LAS __attribute__((address_space(3)))
; __device__ __forceinline__ void phase_prep(const Params& p, LAS unsigned char* lds) {
;     ...
;             for (int c4 = 0; c4 < 16; ++c4)
; #pragma unroll
;                 for (int cc = 0; cc < 4; ++cc) { const float wv = rw[c4][cc]; const LAS f32x4* mp = (const LAS f32x4*)(Mf + (4 * c4 + cc) * 64 + eg * 16);
; #pragma unroll
;                     for (int j4 = 0; j4 < 4; ++j4) { const f32x4 mv = mp[j4]; a[4 * j4 + 0] += wv * mv[0]; a[4 * j4 + 1] += wv * mv[1]; a[4 * j4 + 2] += wv * mv[2]; a[4 * j4 + 3] += wv * mv[3]; } }
	v_fmac_f32_e32 v80, v87, v122
	v_fmac_f32_e32 v79, v87, v123
	v_fmac_f32_e32 v78, v87, v124
	v_fmac_f32_e32 v77, v87, v125
	ds_read_b128 v[122:125], v66 offset:3344
	s_waitcnt lgkmcnt(15)
	v_fmac_f32_e32 v76, v87, v126
	v_fmac_f32_e32 v75, v87, v127
	v_fmac_f32_e32 v74, v87, v128
	v_fmac_f32_e32 v73, v87, v129
	ds_read_b128 v[126:129], v66 offset:3360
	s_waitcnt lgkmcnt(15)
	v_fmac_f32_e32 v72, v87, v130
	v_fmac_f32_e32 v71, v87, v131
	v_fmac_f32_e32 v70, v87, v132
	v_fmac_f32_e32 v69, v87, v133
	ds_read_b128 v[130:133], v66 offset:3376
	s_waitcnt lgkmcnt(15)
	v_fmac_f32_e32 v84, v88, v134
	v_fmac_f32_e32 v83, v88, v135
	v_fmac_f32_e32 v82, v88, v136
	v_fmac_f32_e32 v81, v88, v137
	ds_read_b128 v[134:137], v66 offset:3584
	s_waitcnt lgkmcnt(15)
	v_fmac_f32_e32 v80, v88, v138
	v_fmac_f32_e32 v79, v88, v139
	v_fmac_f32_e32 v78, v88, v140
	v_fmac_f32_e32 v77, v88, v141
	ds_read_b128 v[138:141], v66 offset:3600
	s_waitcnt lgkmcnt(15)
	v_fmac_f32_e32 v76, v88, v142
	v_fmac_f32_e32 v75, v88, v143
	v_fmac_f32_e32 v74, v88, v144
	v_fmac_f32_e32 v73, v88, v145
	ds_read_b128 v[142:145], v66 offset:3616
	s_waitcnt lgkmcnt(15)
	v_fmac_f32_e32 v72, v88, v146
	v_fmac_f32_e32 v71, v88, v147
	v_fmac_f32_e32 v70, v88, v148
	v_fmac_f32_e32 v69, v88, v149
	ds_read_b128 v[146:149], v66 offset:3632
	s_waitcnt lgkmcnt(15)
	v_fmac_f32_e32 v84, v89, v150
	v_fmac_f32_e32 v83, v89, v151
	v_fmac_f32_e32 v82, v89, v152
	v_fmac_f32_e32 v81, v89, v153
	ds_read_b128 v[150:153], v66 offset:3840
	s_waitcnt lgkmcnt(15)
	v_fmac_f32_e32 v80, v89, v158
	v_fmac_f32_e32 v79, v89, v159
	v_fmac_f32_e32 v78, v89, v160
	v_fmac_f32_e32 v77, v89, v161
	ds_read_b128 v[158:161], v66 offset:3856
	s_waitcnt lgkmcnt(15)
	v_fmac_f32_e32 v76, v89, v162
	v_fmac_f32_e32 v75, v89, v163
	v_fmac_f32_e32 v74, v89, v164
	v_fmac_f32_e32 v73, v89, v165
	ds_read_b128 v[162:165], v66 offset:3872
	s_waitcnt lgkmcnt(15)
	v_fmac_f32_e32 v72, v89, v166
	v_fmac_f32_e32 v71, v89, v167
	v_fmac_f32_e32 v70, v89, v168
	v_fmac_f32_e32 v69, v89, v169
	ds_read_b128 v[166:169], v66 offset:3888
	s_waitcnt lgkmcnt(15)
	v_fmac_f32_e32 v84, v52, v102
	v_fmac_f32_e32 v83, v52, v103
	v_fmac_f32_e32 v82, v52, v104
	v_fmac_f32_e32 v81, v52, v105
	ds_read_b128 v[102:105], v66 offset:4096
	s_waitcnt lgkmcnt(15)
	v_fmac_f32_e32 v80, v52, v106
	v_fmac_f32_e32 v79, v52, v107
	v_fmac_f32_e32 v78, v52, v108
	v_fmac_f32_e32 v77, v52, v109
	ds_read_b128 v[106:109], v66 offset:4112
	s_waitcnt lgkmcnt(15)
	v_fmac_f32_e32 v76, v52, v110
	v_fmac_f32_e32 v75, v52, v111
	v_fmac_f32_e32 v74, v52, v112
	v_fmac_f32_e32 v73, v52, v113
	ds_read_b128 v[110:113], v66 offset:4128
	s_waitcnt lgkmcnt(15)
	v_fmac_f32_e32 v72, v52, v114
	v_fmac_f32_e32 v71, v52, v115
	v_fmac_f32_e32 v70, v52, v116
	v_fmac_f32_e32 v69, v52, v117
	ds_read_b128 v[114:117], v66 offset:4144
	s_waitcnt lgkmcnt(15)
	v_fmac_f32_e32 v84, v53, v118
	v_fmac_f32_e32 v83, v53, v119
	v_fmac_f32_e32 v82, v53, v120
	v_fmac_f32_e32 v81, v53, v121
	ds_read_b128 v[118:121], v66 offset:4352
	s_waitcnt lgkmcnt(15)
	v_fmac_f32_e32 v80, v53, v122
	v_fmac_f32_e32 v79, v53, v123
	v_fmac_f32_e32 v78, v53, v124
	v_fmac_f32_e32 v77, v53, v125
	ds_read_b128 v[122:125], v66 offset:4368
	s_waitcnt lgkmcnt(15)
	v_fmac_f32_e32 v76, v53, v126
	v_fmac_f32_e32 v75, v53, v127
	v_fmac_f32_e32 v74, v53, v128
	v_fmac_f32_e32 v73, v53, v129
	ds_read_b128 v[126:129], v66 offset:4384
	s_waitcnt lgkmcnt(15)
	v_fmac_f32_e32 v72, v53, v130
	v_fmac_f32_e32 v71, v53, v131
	v_fmac_f32_e32 v70, v53, v132
	v_fmac_f32_e32 v69, v53, v133
	ds_read_b128 v[130:133], v66 offset:4400
	s_waitcnt lgkmcnt(15)
	v_fmac_f32_e32 v84, v54, v134
	v_fmac_f32_e32 v83, v54, v135
	v_fmac_f32_e32 v82, v54, v136
	v_fmac_f32_e32 v81, v54, v137
	ds_read_b128 v[134:137], v66 offset:4608
	s_waitcnt lgkmcnt(15)
	v_fmac_f32_e32 v80, v54, v138
	v_fmac_f32_e32 v79, v54, v139
	v_fmac_f32_e32 v78, v54, v140
	v_fmac_f32_e32 v77, v54, v141
	ds_read_b128 v[138:141], v66 offset:4624
	s_waitcnt lgkmcnt(15)
	v_fmac_f32_e32 v76, v54, v142
	v_fmac_f32_e32 v75, v54, v143
	v_fmac_f32_e32 v74, v54, v144
	v_fmac_f32_e32 v73, v54, v145
	ds_read_b128 v[142:145], v66 offset:4640
	s_waitcnt lgkmcnt(15)
	v_fmac_f32_e32 v72, v54, v146
	v_fmac_f32_e32 v71, v54, v147
	v_fmac_f32_e32 v70, v54, v148
	v_fmac_f32_e32 v69, v54, v149
	ds_read_b128 v[146:149], v66 offset:4656
	s_waitcnt lgkmcnt(15)
	v_fmac_f32_e32 v84, v55, v150
	v_fmac_f32_e32 v83, v55, v151
	v_fmac_f32_e32 v82, v55, v152
	v_fmac_f32_e32 v81, v55, v153
	ds_read_b128 v[150:153], v66 offset:4864
	s_waitcnt lgkmcnt(15)
	v_fmac_f32_e32 v80, v55, v158
	v_fmac_f32_e32 v79, v55, v159
	v_fmac_f32_e32 v78, v55, v160
	v_fmac_f32_e32 v77, v55, v161
	ds_read_b128 v[158:161], v66 offset:4880
	s_waitcnt lgkmcnt(15)
	v_fmac_f32_e32 v76, v55, v162
	v_fmac_f32_e32 v75, v55, v163
	v_fmac_f32_e32 v74, v55, v164
	v_fmac_f32_e32 v73, v55, v165
	ds_read_b128 v[162:165], v66 offset:4896
	s_waitcnt lgkmcnt(15)
	v_fmac_f32_e32 v72, v55, v166
	v_fmac_f32_e32 v71, v55, v167
	v_fmac_f32_e32 v70, v55, v168
	v_fmac_f32_e32 v69, v55, v169
	ds_read_b128 v[166:169], v66 offset:4912
	s_waitcnt lgkmcnt(15)
	v_fmac_f32_e32 v84, v48, v102
	v_fmac_f32_e32 v83, v48, v103
	v_fmac_f32_e32 v82, v48, v104
	v_fmac_f32_e32 v81, v48, v105
	ds_read_b128 v[102:105], v66 offset:5120
	s_waitcnt lgkmcnt(15)
	v_fmac_f32_e32 v80, v48, v106
	v_fmac_f32_e32 v79, v48, v107
	v_fmac_f32_e32 v78, v48, v108
	v_fmac_f32_e32 v77, v48, v109
	ds_read_b128 v[106:109], v66 offset:5136
	s_waitcnt lgkmcnt(15)
	v_fmac_f32_e32 v76, v48, v110
	v_fmac_f32_e32 v75, v48, v111
	v_fmac_f32_e32 v74, v48, v112
	v_fmac_f32_e32 v73, v48, v113
	ds_read_b128 v[110:113], v66 offset:5152
	s_waitcnt lgkmcnt(15)
; #define LAS __attribute__((address_space(3)))
; __device__ __forceinline__ void phase_prep(const Params& p, LAS unsigned char* lds) {
;     ...
;             for (int c4 = 0; c4 < 16; ++c4)
; #pragma unroll
;                 for (int cc = 0; cc < 4; ++cc) { const float wv = rw[c4][cc]; const LAS f32x4* mp = (const LAS f32x4*)(Mf + (4 * c4 + cc) * 64 + eg * 16);
; #pragma unroll
;                     for (int j4 = 0; j4 < 4; ++j4) { const f32x4 mv = mp[j4]; a[4 * j4 + 0] += wv * mv[0]; a[4 * j4 + 1] += wv * mv[1]; a[4 * j4 + 2] += wv * mv[2]; a[4 * j4 + 3] += wv * mv[3]; } }
	v_fmac_f32_e32 v72, v48, v114
	v_fmac_f32_e32 v71, v48, v115
	v_fmac_f32_e32 v70, v48, v116
	v_fmac_f32_e32 v69, v48, v117
	ds_read_b128 v[114:117], v66 offset:5168
	s_waitcnt lgkmcnt(15)
	v_fmac_f32_e32 v84, v49, v118
	v_fmac_f32_e32 v83, v49, v119
	v_fmac_f32_e32 v82, v49, v120
	v_fmac_f32_e32 v81, v49, v121
	ds_read_b128 v[118:121], v66 offset:5376
	s_waitcnt lgkmcnt(15)
	v_fmac_f32_e32 v80, v49, v122
	v_fmac_f32_e32 v79, v49, v123
	v_fmac_f32_e32 v78, v49, v124
	v_fmac_f32_e32 v77, v49, v125
	ds_read_b128 v[122:125], v66 offset:5392
	s_waitcnt lgkmcnt(15)
	v_fmac_f32_e32 v76, v49, v126
	v_fmac_f32_e32 v75, v49, v127
	v_fmac_f32_e32 v74, v49, v128
	v_fmac_f32_e32 v73, v49, v129
	ds_read_b128 v[126:129], v66 offset:5408
	s_waitcnt lgkmcnt(15)
	v_fmac_f32_e32 v72, v49, v130
	v_fmac_f32_e32 v71, v49, v131
	v_fmac_f32_e32 v70, v49, v132
	v_fmac_f32_e32 v69, v49, v133
	ds_read_b128 v[130:133], v66 offset:5424
	s_waitcnt lgkmcnt(15)
	v_fmac_f32_e32 v84, v50, v134
	v_fmac_f32_e32 v83, v50, v135
	v_fmac_f32_e32 v82, v50, v136
	v_fmac_f32_e32 v81, v50, v137
	ds_read_b128 v[134:137], v66 offset:5632
	s_waitcnt lgkmcnt(15)
	v_fmac_f32_e32 v80, v50, v138
	v_fmac_f32_e32 v79, v50, v139
	v_fmac_f32_e32 v78, v50, v140
	v_fmac_f32_e32 v77, v50, v141
	ds_read_b128 v[138:141], v66 offset:5648
	s_waitcnt lgkmcnt(15)
	v_fmac_f32_e32 v76, v50, v142
	v_fmac_f32_e32 v75, v50, v143
	v_fmac_f32_e32 v74, v50, v144
	v_fmac_f32_e32 v73, v50, v145
	ds_read_b128 v[142:145], v66 offset:5664
	s_waitcnt lgkmcnt(15)
	v_fmac_f32_e32 v72, v50, v146
	v_fmac_f32_e32 v71, v50, v147
	v_fmac_f32_e32 v70, v50, v148
	v_fmac_f32_e32 v69, v50, v149
	ds_read_b128 v[146:149], v66 offset:5680
	s_waitcnt lgkmcnt(15)
	v_fmac_f32_e32 v84, v51, v150
	v_fmac_f32_e32 v83, v51, v151
	v_fmac_f32_e32 v82, v51, v152
	v_fmac_f32_e32 v81, v51, v153
	ds_read_b128 v[150:153], v66 offset:5888
	s_waitcnt lgkmcnt(15)
	v_fmac_f32_e32 v80, v51, v158
	v_fmac_f32_e32 v79, v51, v159
	v_fmac_f32_e32 v78, v51, v160
	v_fmac_f32_e32 v77, v51, v161
	ds_read_b128 v[158:161], v66 offset:5904
	s_waitcnt lgkmcnt(15)
	v_fmac_f32_e32 v76, v51, v162
	v_fmac_f32_e32 v75, v51, v163
	v_fmac_f32_e32 v74, v51, v164
	v_fmac_f32_e32 v73, v51, v165
	ds_read_b128 v[162:165], v66 offset:5920
	s_waitcnt lgkmcnt(15)
	v_fmac_f32_e32 v72, v51, v166
	v_fmac_f32_e32 v71, v51, v167
	v_fmac_f32_e32 v70, v51, v168
	v_fmac_f32_e32 v69, v51, v169
	ds_read_b128 v[166:169], v66 offset:5936
	s_waitcnt lgkmcnt(15)
	v_fmac_f32_e32 v84, v44, v102
	v_fmac_f32_e32 v83, v44, v103
	v_fmac_f32_e32 v82, v44, v104
	v_fmac_f32_e32 v81, v44, v105
	ds_read_b128 v[102:105], v66 offset:6144
	s_waitcnt lgkmcnt(15)
	v_fmac_f32_e32 v80, v44, v106
	v_fmac_f32_e32 v79, v44, v107
	v_fmac_f32_e32 v78, v44, v108
	v_fmac_f32_e32 v77, v44, v109
	ds_read_b128 v[106:109], v66 offset:6160
	s_waitcnt lgkmcnt(15)
	v_fmac_f32_e32 v76, v44, v110
	v_fmac_f32_e32 v75, v44, v111
	v_fmac_f32_e32 v74, v44, v112
	v_fmac_f32_e32 v73, v44, v113
	ds_read_b128 v[110:113], v66 offset:6176
	s_waitcnt lgkmcnt(15)
	v_fmac_f32_e32 v72, v44, v114
	v_fmac_f32_e32 v71, v44, v115
	v_fmac_f32_e32 v70, v44, v116
	v_fmac_f32_e32 v69, v44, v117
	ds_read_b128 v[114:117], v66 offset:6192
	s_waitcnt lgkmcnt(15)
	v_fmac_f32_e32 v84, v45, v118
	v_fmac_f32_e32 v83, v45, v119
	v_fmac_f32_e32 v82, v45, v120
	v_fmac_f32_e32 v81, v45, v121
	ds_read_b128 v[118:121], v66 offset:6400
	s_waitcnt lgkmcnt(15)
	v_fmac_f32_e32 v80, v45, v122
	v_fmac_f32_e32 v79, v45, v123
	v_fmac_f32_e32 v78, v45, v124
	v_fmac_f32_e32 v77, v45, v125
	ds_read_b128 v[122:125], v66 offset:6416
	s_waitcnt lgkmcnt(15)
	v_fmac_f32_e32 v76, v45, v126
	v_fmac_f32_e32 v75, v45, v127
	v_fmac_f32_e32 v74, v45, v128
	v_fmac_f32_e32 v73, v45, v129
	ds_read_b128 v[126:129], v66 offset:6432
	s_waitcnt lgkmcnt(15)
	v_fmac_f32_e32 v72, v45, v130
	v_fmac_f32_e32 v71, v45, v131
	v_fmac_f32_e32 v70, v45, v132
	v_fmac_f32_e32 v69, v45, v133
	ds_read_b128 v[130:133], v66 offset:6448
	s_waitcnt lgkmcnt(15)
	v_fmac_f32_e32 v84, v46, v134
	v_fmac_f32_e32 v83, v46, v135
	v_fmac_f32_e32 v82, v46, v136
	v_fmac_f32_e32 v81, v46, v137
	ds_read_b128 v[134:137], v66 offset:6656
	s_waitcnt lgkmcnt(15)
	v_fmac_f32_e32 v80, v46, v138
	v_fmac_f32_e32 v79, v46, v139
	v_fmac_f32_e32 v78, v46, v140
	v_fmac_f32_e32 v77, v46, v141
	ds_read_b128 v[138:141], v66 offset:6672
	s_waitcnt lgkmcnt(15)
	v_fmac_f32_e32 v76, v46, v142
	v_fmac_f32_e32 v75, v46, v143
	v_fmac_f32_e32 v74, v46, v144
	v_fmac_f32_e32 v73, v46, v145
	ds_read_b128 v[142:145], v66 offset:6688
	s_waitcnt lgkmcnt(15)
	v_fmac_f32_e32 v72, v46, v146
	v_fmac_f32_e32 v71, v46, v147
	v_fmac_f32_e32 v70, v46, v148
	v_fmac_f32_e32 v69, v46, v149
	ds_read_b128 v[146:149], v66 offset:6704
	s_waitcnt lgkmcnt(15)
	v_fmac_f32_e32 v84, v47, v150
	v_fmac_f32_e32 v83, v47, v151
	v_fmac_f32_e32 v82, v47, v152
	v_fmac_f32_e32 v81, v47, v153
	ds_read_b128 v[150:153], v66 offset:6912
	s_waitcnt lgkmcnt(15)
	v_fmac_f32_e32 v80, v47, v158
	v_fmac_f32_e32 v79, v47, v159
	v_fmac_f32_e32 v78, v47, v160
	v_fmac_f32_e32 v77, v47, v161
	ds_read_b128 v[158:161], v66 offset:6928
	s_waitcnt lgkmcnt(15)
	v_fmac_f32_e32 v76, v47, v162
	v_fmac_f32_e32 v75, v47, v163
	v_fmac_f32_e32 v74, v47, v164
	v_fmac_f32_e32 v73, v47, v165
	ds_read_b128 v[162:165], v66 offset:6944
	s_waitcnt lgkmcnt(15)
	v_fmac_f32_e32 v72, v47, v166
	v_fmac_f32_e32 v71, v47, v167
	v_fmac_f32_e32 v70, v47, v168
	v_fmac_f32_e32 v69, v47, v169
	ds_read_b128 v[166:169], v66 offset:6960
	s_waitcnt lgkmcnt(15)
	v_fmac_f32_e32 v84, v40, v102
	v_fmac_f32_e32 v83, v40, v103
	v_fmac_f32_e32 v82, v40, v104
	v_fmac_f32_e32 v81, v40, v105
	ds_read_b128 v[102:105], v66 offset:7168
	s_waitcnt lgkmcnt(15)
; #define LAS __attribute__((address_space(3)))
; __device__ __forceinline__ void phase_prep(const Params& p, LAS unsigned char* lds) {
;     ...
;             for (int c4 = 0; c4 < 16; ++c4)
; #pragma unroll
;                 for (int cc = 0; cc < 4; ++cc) { const float wv = rw[c4][cc]; const LAS f32x4* mp = (const LAS f32x4*)(Mf + (4 * c4 + cc) * 64 + eg * 16);
; #pragma unroll
;                     for (int j4 = 0; j4 < 4; ++j4) { const f32x4 mv = mp[j4]; a[4 * j4 + 0] += wv * mv[0]; a[4 * j4 + 1] += wv * mv[1]; a[4 * j4 + 2] += wv * mv[2]; a[4 * j4 + 3] += wv * mv[3]; } }
	v_fmac_f32_e32 v80, v40, v106
	v_fmac_f32_e32 v79, v40, v107
	v_fmac_f32_e32 v78, v40, v108
	v_fmac_f32_e32 v77, v40, v109
	ds_read_b128 v[106:109], v66 offset:7184
	s_waitcnt lgkmcnt(15)
	v_fmac_f32_e32 v76, v40, v110
	v_fmac_f32_e32 v75, v40, v111
	v_fmac_f32_e32 v74, v40, v112
	v_fmac_f32_e32 v73, v40, v113
	ds_read_b128 v[110:113], v66 offset:7200
	s_waitcnt lgkmcnt(15)
	v_fmac_f32_e32 v72, v40, v114
	v_fmac_f32_e32 v71, v40, v115
	v_fmac_f32_e32 v70, v40, v116
	v_fmac_f32_e32 v69, v40, v117
	ds_read_b128 v[114:117], v66 offset:7216
	s_waitcnt lgkmcnt(15)
	v_fmac_f32_e32 v84, v41, v118
	v_fmac_f32_e32 v83, v41, v119
	v_fmac_f32_e32 v82, v41, v120
	v_fmac_f32_e32 v81, v41, v121
	ds_read_b128 v[118:121], v66 offset:7424
	s_waitcnt lgkmcnt(15)
	v_fmac_f32_e32 v80, v41, v122
	v_fmac_f32_e32 v79, v41, v123
	v_fmac_f32_e32 v78, v41, v124
	v_fmac_f32_e32 v77, v41, v125
	ds_read_b128 v[122:125], v66 offset:7440
	s_waitcnt lgkmcnt(15)
	v_fmac_f32_e32 v76, v41, v126
	v_fmac_f32_e32 v75, v41, v127
	v_fmac_f32_e32 v74, v41, v128
	v_fmac_f32_e32 v73, v41, v129
	ds_read_b128 v[126:129], v66 offset:7456
	s_waitcnt lgkmcnt(15)
	v_fmac_f32_e32 v72, v41, v130
	v_fmac_f32_e32 v71, v41, v131
	v_fmac_f32_e32 v70, v41, v132
	v_fmac_f32_e32 v69, v41, v133
	ds_read_b128 v[130:133], v66 offset:7472
	s_waitcnt lgkmcnt(15)
	v_fmac_f32_e32 v84, v42, v134
	v_fmac_f32_e32 v83, v42, v135
	v_fmac_f32_e32 v82, v42, v136
	v_fmac_f32_e32 v81, v42, v137
	ds_read_b128 v[134:137], v66 offset:7680
	s_waitcnt lgkmcnt(15)
	v_fmac_f32_e32 v80, v42, v138
	v_fmac_f32_e32 v79, v42, v139
	v_fmac_f32_e32 v78, v42, v140
	v_fmac_f32_e32 v77, v42, v141
	ds_read_b128 v[138:141], v66 offset:7696
	s_waitcnt lgkmcnt(15)
	v_fmac_f32_e32 v76, v42, v142
	v_fmac_f32_e32 v75, v42, v143
	v_fmac_f32_e32 v74, v42, v144
	v_fmac_f32_e32 v73, v42, v145
	ds_read_b128 v[142:145], v66 offset:7712
	s_waitcnt lgkmcnt(15)
	v_fmac_f32_e32 v72, v42, v146
	v_fmac_f32_e32 v71, v42, v147
	v_fmac_f32_e32 v70, v42, v148
	v_fmac_f32_e32 v69, v42, v149
	ds_read_b128 v[146:149], v66 offset:7728
	s_waitcnt lgkmcnt(15)
	v_fmac_f32_e32 v84, v43, v150
	v_fmac_f32_e32 v83, v43, v151
	v_fmac_f32_e32 v82, v43, v152
	v_fmac_f32_e32 v81, v43, v153
	ds_read_b128 v[150:153], v66 offset:7936
	s_waitcnt lgkmcnt(15)
	v_fmac_f32_e32 v80, v43, v158
	v_fmac_f32_e32 v79, v43, v159
	v_fmac_f32_e32 v78, v43, v160
	v_fmac_f32_e32 v77, v43, v161
	ds_read_b128 v[158:161], v66 offset:7952
	s_waitcnt lgkmcnt(15)
	v_fmac_f32_e32 v76, v43, v162
	v_fmac_f32_e32 v75, v43, v163
	v_fmac_f32_e32 v74, v43, v164
	v_fmac_f32_e32 v73, v43, v165
	ds_read_b128 v[162:165], v66 offset:7968
	s_waitcnt lgkmcnt(15)
	v_fmac_f32_e32 v72, v43, v166
	v_fmac_f32_e32 v71, v43, v167
	v_fmac_f32_e32 v70, v43, v168
	v_fmac_f32_e32 v69, v43, v169
	ds_read_b128 v[166:169], v66 offset:7984
	s_waitcnt lgkmcnt(15)
	v_fmac_f32_e32 v84, v36, v102
	v_fmac_f32_e32 v83, v36, v103
	v_fmac_f32_e32 v82, v36, v104
	v_fmac_f32_e32 v81, v36, v105
	ds_read_b128 v[102:105], v66 offset:8192
	s_waitcnt lgkmcnt(15)
	v_fmac_f32_e32 v80, v36, v106
	v_fmac_f32_e32 v79, v36, v107
	v_fmac_f32_e32 v78, v36, v108
	v_fmac_f32_e32 v77, v36, v109
	ds_read_b128 v[106:109], v66 offset:8208
	s_waitcnt lgkmcnt(15)
	v_fmac_f32_e32 v76, v36, v110
	v_fmac_f32_e32 v75, v36, v111
	v_fmac_f32_e32 v74, v36, v112
	v_fmac_f32_e32 v73, v36, v113
	ds_read_b128 v[110:113], v66 offset:8224
	s_waitcnt lgkmcnt(15)
	v_fmac_f32_e32 v72, v36, v114
	v_fmac_f32_e32 v71, v36, v115
	v_fmac_f32_e32 v70, v36, v116
	v_fmac_f32_e32 v69, v36, v117
	ds_read_b128 v[114:117], v66 offset:8240
	s_waitcnt lgkmcnt(15)
	v_fmac_f32_e32 v84, v37, v118
	v_fmac_f32_e32 v83, v37, v119
	v_fmac_f32_e32 v82, v37, v120
	v_fmac_f32_e32 v81, v37, v121
	ds_read_b128 v[118:121], v66 offset:8448
	s_waitcnt lgkmcnt(15)
	v_fmac_f32_e32 v80, v37, v122
	v_fmac_f32_e32 v79, v37, v123
	v_fmac_f32_e32 v78, v37, v124
	v_fmac_f32_e32 v77, v37, v125
	ds_read_b128 v[122:125], v66 offset:8464
	s_waitcnt lgkmcnt(15)
	v_fmac_f32_e32 v76, v37, v126
	v_fmac_f32_e32 v75, v37, v127
	v_fmac_f32_e32 v74, v37, v128
	v_fmac_f32_e32 v73, v37, v129
	ds_read_b128 v[126:129], v66 offset:8480
	s_waitcnt lgkmcnt(15)
	v_fmac_f32_e32 v72, v37, v130
	v_fmac_f32_e32 v71, v37, v131
	v_fmac_f32_e32 v70, v37, v132
	v_fmac_f32_e32 v69, v37, v133
	ds_read_b128 v[130:133], v66 offset:8496
	s_waitcnt lgkmcnt(15)
	v_fmac_f32_e32 v84, v38, v134
	v_fmac_f32_e32 v83, v38, v135
	v_fmac_f32_e32 v82, v38, v136
	v_fmac_f32_e32 v81, v38, v137
	ds_read_b128 v[134:137], v66 offset:8704
	s_waitcnt lgkmcnt(15)
	v_fmac_f32_e32 v80, v38, v138
	v_fmac_f32_e32 v79, v38, v139
	v_fmac_f32_e32 v78, v38, v140
	v_fmac_f32_e32 v77, v38, v141
	ds_read_b128 v[138:141], v66 offset:8720
	s_waitcnt lgkmcnt(15)
	v_fmac_f32_e32 v76, v38, v142
	v_fmac_f32_e32 v75, v38, v143
	v_fmac_f32_e32 v74, v38, v144
	v_fmac_f32_e32 v73, v38, v145
	ds_read_b128 v[142:145], v66 offset:8736
	s_waitcnt lgkmcnt(15)
	v_fmac_f32_e32 v72, v38, v146
	v_fmac_f32_e32 v71, v38, v147
	v_fmac_f32_e32 v70, v38, v148
	v_fmac_f32_e32 v69, v38, v149
	ds_read_b128 v[146:149], v66 offset:8752
	s_waitcnt lgkmcnt(15)
	v_fmac_f32_e32 v84, v39, v150
	v_fmac_f32_e32 v83, v39, v151
	v_fmac_f32_e32 v82, v39, v152
	v_fmac_f32_e32 v81, v39, v153
	ds_read_b128 v[150:153], v66 offset:8960
	s_waitcnt lgkmcnt(15)
	v_fmac_f32_e32 v80, v39, v158
	v_fmac_f32_e32 v79, v39, v159
	v_fmac_f32_e32 v78, v39, v160
	v_fmac_f32_e32 v77, v39, v161
	ds_read_b128 v[158:161], v66 offset:8976
	s_waitcnt lgkmcnt(15)
	v_fmac_f32_e32 v76, v39, v162
	v_fmac_f32_e32 v75, v39, v163
	v_fmac_f32_e32 v74, v39, v164
	v_fmac_f32_e32 v73, v39, v165
	ds_read_b128 v[162:165], v66 offset:8992
	s_waitcnt lgkmcnt(15)
; #define LAS __attribute__((address_space(3)))
; __device__ __forceinline__ void phase_prep(const Params& p, LAS unsigned char* lds) {
;     ...
;             for (int c4 = 0; c4 < 16; ++c4)
; #pragma unroll
;                 for (int cc = 0; cc < 4; ++cc) { const float wv = rw[c4][cc]; const LAS f32x4* mp = (const LAS f32x4*)(Mf + (4 * c4 + cc) * 64 + eg * 16);
; #pragma unroll
;                     for (int j4 = 0; j4 < 4; ++j4) { const f32x4 mv = mp[j4]; a[4 * j4 + 0] += wv * mv[0]; a[4 * j4 + 1] += wv * mv[1]; a[4 * j4 + 2] += wv * mv[2]; a[4 * j4 + 3] += wv * mv[3]; } }
	v_fmac_f32_e32 v72, v39, v166
	v_fmac_f32_e32 v71, v39, v167
	v_fmac_f32_e32 v70, v39, v168
	v_fmac_f32_e32 v69, v39, v169
	ds_read_b128 v[166:169], v66 offset:9008
	s_waitcnt lgkmcnt(15)
	v_fmac_f32_e32 v84, v32, v102
	v_fmac_f32_e32 v83, v32, v103
	v_fmac_f32_e32 v82, v32, v104
	v_fmac_f32_e32 v81, v32, v105
	ds_read_b128 v[102:105], v66 offset:9216
	s_waitcnt lgkmcnt(15)
	v_fmac_f32_e32 v80, v32, v106
	v_fmac_f32_e32 v79, v32, v107
	v_fmac_f32_e32 v78, v32, v108
	v_fmac_f32_e32 v77, v32, v109
	ds_read_b128 v[106:109], v66 offset:9232
	s_waitcnt lgkmcnt(15)
	v_fmac_f32_e32 v76, v32, v110
	v_fmac_f32_e32 v75, v32, v111
	v_fmac_f32_e32 v74, v32, v112
	v_fmac_f32_e32 v73, v32, v113
	ds_read_b128 v[110:113], v66 offset:9248
	s_waitcnt lgkmcnt(15)
	v_fmac_f32_e32 v72, v32, v114
	v_fmac_f32_e32 v71, v32, v115
	v_fmac_f32_e32 v70, v32, v116
	v_fmac_f32_e32 v69, v32, v117
	ds_read_b128 v[114:117], v66 offset:9264
	s_waitcnt lgkmcnt(15)
	v_fmac_f32_e32 v84, v33, v118
	v_fmac_f32_e32 v83, v33, v119
	v_fmac_f32_e32 v82, v33, v120
	v_fmac_f32_e32 v81, v33, v121
	ds_read_b128 v[118:121], v66 offset:9472
	s_waitcnt lgkmcnt(15)
	v_fmac_f32_e32 v80, v33, v122
	v_fmac_f32_e32 v79, v33, v123
	v_fmac_f32_e32 v78, v33, v124
	v_fmac_f32_e32 v77, v33, v125
	ds_read_b128 v[122:125], v66 offset:9488
	s_waitcnt lgkmcnt(15)
	v_fmac_f32_e32 v76, v33, v126
	v_fmac_f32_e32 v75, v33, v127
	v_fmac_f32_e32 v74, v33, v128
	v_fmac_f32_e32 v73, v33, v129
	ds_read_b128 v[126:129], v66 offset:9504
	s_waitcnt lgkmcnt(15)
	v_fmac_f32_e32 v72, v33, v130
	v_fmac_f32_e32 v71, v33, v131
	v_fmac_f32_e32 v70, v33, v132
	v_fmac_f32_e32 v69, v33, v133
	ds_read_b128 v[130:133], v66 offset:9520
	s_waitcnt lgkmcnt(15)
	v_fmac_f32_e32 v84, v34, v134
	v_fmac_f32_e32 v83, v34, v135
	v_fmac_f32_e32 v82, v34, v136
	v_fmac_f32_e32 v81, v34, v137
	ds_read_b128 v[134:137], v66 offset:9728
	s_waitcnt lgkmcnt(15)
	v_fmac_f32_e32 v80, v34, v138
	v_fmac_f32_e32 v79, v34, v139
	v_fmac_f32_e32 v78, v34, v140
	v_fmac_f32_e32 v77, v34, v141
	ds_read_b128 v[138:141], v66 offset:9744
	s_waitcnt lgkmcnt(15)
	v_fmac_f32_e32 v76, v34, v142
	v_fmac_f32_e32 v75, v34, v143
	v_fmac_f32_e32 v74, v34, v144
	v_fmac_f32_e32 v73, v34, v145
	ds_read_b128 v[142:145], v66 offset:9760
	s_waitcnt lgkmcnt(15)
	v_fmac_f32_e32 v72, v34, v146
	v_fmac_f32_e32 v71, v34, v147
	v_fmac_f32_e32 v70, v34, v148
	v_fmac_f32_e32 v69, v34, v149
	ds_read_b128 v[146:149], v66 offset:9776
	s_waitcnt lgkmcnt(15)
	v_fmac_f32_e32 v84, v35, v150
	v_fmac_f32_e32 v83, v35, v151
	v_fmac_f32_e32 v82, v35, v152
	v_fmac_f32_e32 v81, v35, v153
	ds_read_b128 v[150:153], v66 offset:9984
	s_waitcnt lgkmcnt(15)
	v_fmac_f32_e32 v80, v35, v158
	v_fmac_f32_e32 v79, v35, v159
	v_fmac_f32_e32 v78, v35, v160
	v_fmac_f32_e32 v77, v35, v161
	ds_read_b128 v[158:161], v66 offset:10000
	s_waitcnt lgkmcnt(15)
	v_fmac_f32_e32 v76, v35, v162
	v_fmac_f32_e32 v75, v35, v163
	v_fmac_f32_e32 v74, v35, v164
	v_fmac_f32_e32 v73, v35, v165
	ds_read_b128 v[162:165], v66 offset:10016
	s_waitcnt lgkmcnt(15)
	v_fmac_f32_e32 v72, v35, v166
	v_fmac_f32_e32 v71, v35, v167
	v_fmac_f32_e32 v70, v35, v168
	v_fmac_f32_e32 v69, v35, v169
	ds_read_b128 v[166:169], v66 offset:10032
	s_waitcnt lgkmcnt(15)
	v_fmac_f32_e32 v84, v28, v102
	v_fmac_f32_e32 v83, v28, v103
	v_fmac_f32_e32 v82, v28, v104
	v_fmac_f32_e32 v81, v28, v105
	ds_read_b128 v[102:105], v66 offset:10240
	s_waitcnt lgkmcnt(15)
	v_fmac_f32_e32 v80, v28, v106
	v_fmac_f32_e32 v79, v28, v107
	v_fmac_f32_e32 v78, v28, v108
	v_fmac_f32_e32 v77, v28, v109
	ds_read_b128 v[106:109], v66 offset:10256
	s_waitcnt lgkmcnt(15)
	v_fmac_f32_e32 v76, v28, v110
	v_fmac_f32_e32 v75, v28, v111
	v_fmac_f32_e32 v74, v28, v112
	v_fmac_f32_e32 v73, v28, v113
	ds_read_b128 v[110:113], v66 offset:10272
	s_waitcnt lgkmcnt(15)
	v_fmac_f32_e32 v72, v28, v114
	v_fmac_f32_e32 v71, v28, v115
	v_fmac_f32_e32 v70, v28, v116
	v_fmac_f32_e32 v69, v28, v117
	ds_read_b128 v[114:117], v66 offset:10288
	s_waitcnt lgkmcnt(15)
	v_fmac_f32_e32 v84, v29, v118
	v_fmac_f32_e32 v83, v29, v119
	v_fmac_f32_e32 v82, v29, v120
	v_fmac_f32_e32 v81, v29, v121
	ds_read_b128 v[118:121], v66 offset:10496
	s_waitcnt lgkmcnt(15)
	v_fmac_f32_e32 v80, v29, v122
	v_fmac_f32_e32 v79, v29, v123
	v_fmac_f32_e32 v78, v29, v124
	v_fmac_f32_e32 v77, v29, v125
	ds_read_b128 v[122:125], v66 offset:10512
	s_waitcnt lgkmcnt(15)
	v_fmac_f32_e32 v76, v29, v126
	v_fmac_f32_e32 v75, v29, v127
	v_fmac_f32_e32 v74, v29, v128
	v_fmac_f32_e32 v73, v29, v129
	ds_read_b128 v[126:129], v66 offset:10528
	s_waitcnt lgkmcnt(15)
	v_fmac_f32_e32 v72, v29, v130
	v_fmac_f32_e32 v71, v29, v131
	v_fmac_f32_e32 v70, v29, v132
	v_fmac_f32_e32 v69, v29, v133
	ds_read_b128 v[130:133], v66 offset:10544
	s_waitcnt lgkmcnt(15)
	v_fmac_f32_e32 v84, v30, v134
	v_fmac_f32_e32 v83, v30, v135
	v_fmac_f32_e32 v82, v30, v136
	v_fmac_f32_e32 v81, v30, v137
	ds_read_b128 v[134:137], v66 offset:10752
	s_waitcnt lgkmcnt(15)
	v_fmac_f32_e32 v80, v30, v138
	v_fmac_f32_e32 v79, v30, v139
	v_fmac_f32_e32 v78, v30, v140
	v_fmac_f32_e32 v77, v30, v141
	ds_read_b128 v[138:141], v66 offset:10768
	s_waitcnt lgkmcnt(15)
	v_fmac_f32_e32 v76, v30, v142
	v_fmac_f32_e32 v75, v30, v143
	v_fmac_f32_e32 v74, v30, v144
	v_fmac_f32_e32 v73, v30, v145
	ds_read_b128 v[142:145], v66 offset:10784
	s_waitcnt lgkmcnt(15)
	v_fmac_f32_e32 v72, v30, v146
	v_fmac_f32_e32 v71, v30, v147
	v_fmac_f32_e32 v70, v30, v148
	v_fmac_f32_e32 v69, v30, v149
	ds_read_b128 v[146:149], v66 offset:10800
	s_waitcnt lgkmcnt(15)
	v_fmac_f32_e32 v84, v31, v150
	v_fmac_f32_e32 v83, v31, v151
	v_fmac_f32_e32 v82, v31, v152
	v_fmac_f32_e32 v81, v31, v153
	ds_read_b128 v[150:153], v66 offset:11008
	s_waitcnt lgkmcnt(15)
; #define LAS __attribute__((address_space(3)))
; __device__ __forceinline__ void phase_prep(const Params& p, LAS unsigned char* lds) {
;     ...
;             for (int c4 = 0; c4 < 16; ++c4)
; #pragma unroll
;                 for (int cc = 0; cc < 4; ++cc) { const float wv = rw[c4][cc]; const LAS f32x4* mp = (const LAS f32x4*)(Mf + (4 * c4 + cc) * 64 + eg * 16);
; #pragma unroll
;                     for (int j4 = 0; j4 < 4; ++j4) { const f32x4 mv = mp[j4]; a[4 * j4 + 0] += wv * mv[0]; a[4 * j4 + 1] += wv * mv[1]; a[4 * j4 + 2] += wv * mv[2]; a[4 * j4 + 3] += wv * mv[3]; } }
	v_fmac_f32_e32 v80, v31, v158
	v_fmac_f32_e32 v79, v31, v159
	v_fmac_f32_e32 v78, v31, v160
	v_fmac_f32_e32 v77, v31, v161
	ds_read_b128 v[158:161], v66 offset:11024
	s_waitcnt lgkmcnt(15)
	v_fmac_f32_e32 v76, v31, v162
	v_fmac_f32_e32 v75, v31, v163
	v_fmac_f32_e32 v74, v31, v164
	v_fmac_f32_e32 v73, v31, v165
	ds_read_b128 v[162:165], v66 offset:11040
	s_waitcnt lgkmcnt(15)
	v_fmac_f32_e32 v72, v31, v166
	v_fmac_f32_e32 v71, v31, v167
	v_fmac_f32_e32 v70, v31, v168
	v_fmac_f32_e32 v69, v31, v169
	ds_read_b128 v[166:169], v66 offset:11056
	s_waitcnt lgkmcnt(15)
	v_fmac_f32_e32 v84, v24, v102
	v_fmac_f32_e32 v83, v24, v103
	v_fmac_f32_e32 v82, v24, v104
	v_fmac_f32_e32 v81, v24, v105
	ds_read_b128 v[102:105], v66 offset:11264
	s_waitcnt lgkmcnt(15)
	v_fmac_f32_e32 v80, v24, v106
	v_fmac_f32_e32 v79, v24, v107
	v_fmac_f32_e32 v78, v24, v108
	v_fmac_f32_e32 v77, v24, v109
	ds_read_b128 v[106:109], v66 offset:11280
	s_waitcnt lgkmcnt(15)
	v_fmac_f32_e32 v76, v24, v110
	v_fmac_f32_e32 v75, v24, v111
	v_fmac_f32_e32 v74, v24, v112
	v_fmac_f32_e32 v73, v24, v113
	ds_read_b128 v[110:113], v66 offset:11296
	s_waitcnt lgkmcnt(15)
	v_fmac_f32_e32 v72, v24, v114
	v_fmac_f32_e32 v71, v24, v115
	v_fmac_f32_e32 v70, v24, v116
	v_fmac_f32_e32 v69, v24, v117
	ds_read_b128 v[114:117], v66 offset:11312
	s_waitcnt lgkmcnt(15)
	v_fmac_f32_e32 v84, v25, v118
	v_fmac_f32_e32 v83, v25, v119
	v_fmac_f32_e32 v82, v25, v120
	v_fmac_f32_e32 v81, v25, v121
	ds_read_b128 v[118:121], v66 offset:11520
	s_waitcnt lgkmcnt(15)
	v_fmac_f32_e32 v80, v25, v122
	v_fmac_f32_e32 v79, v25, v123
	v_fmac_f32_e32 v78, v25, v124
	v_fmac_f32_e32 v77, v25, v125
	ds_read_b128 v[122:125], v66 offset:11536
	s_waitcnt lgkmcnt(15)
	v_fmac_f32_e32 v76, v25, v126
	v_fmac_f32_e32 v75, v25, v127
	v_fmac_f32_e32 v74, v25, v128
	v_fmac_f32_e32 v73, v25, v129
	ds_read_b128 v[126:129], v66 offset:11552
	s_waitcnt lgkmcnt(15)
	v_fmac_f32_e32 v72, v25, v130
	v_fmac_f32_e32 v71, v25, v131
	v_fmac_f32_e32 v70, v25, v132
	v_fmac_f32_e32 v69, v25, v133
	ds_read_b128 v[130:133], v66 offset:11568
	s_waitcnt lgkmcnt(15)
	v_fmac_f32_e32 v84, v26, v134
	v_fmac_f32_e32 v83, v26, v135
	v_fmac_f32_e32 v82, v26, v136
	v_fmac_f32_e32 v81, v26, v137
	ds_read_b128 v[134:137], v66 offset:11776
	s_waitcnt lgkmcnt(15)
	v_fmac_f32_e32 v80, v26, v138
	v_fmac_f32_e32 v79, v26, v139
	v_fmac_f32_e32 v78, v26, v140
	v_fmac_f32_e32 v77, v26, v141
	ds_read_b128 v[138:141], v66 offset:11792
	s_waitcnt lgkmcnt(15)
	v_fmac_f32_e32 v76, v26, v142
	v_fmac_f32_e32 v75, v26, v143
	v_fmac_f32_e32 v74, v26, v144
	v_fmac_f32_e32 v73, v26, v145
	ds_read_b128 v[142:145], v66 offset:11808
	s_waitcnt lgkmcnt(15)
	v_fmac_f32_e32 v72, v26, v146
	v_fmac_f32_e32 v71, v26, v147
	v_fmac_f32_e32 v70, v26, v148
	v_fmac_f32_e32 v69, v26, v149
	ds_read_b128 v[146:149], v66 offset:11824
	s_waitcnt lgkmcnt(15)
	v_fmac_f32_e32 v84, v27, v150
	v_fmac_f32_e32 v83, v27, v151
	v_fmac_f32_e32 v82, v27, v152
	v_fmac_f32_e32 v81, v27, v153
	ds_read_b128 v[150:153], v66 offset:12032
	s_waitcnt lgkmcnt(15)
	v_fmac_f32_e32 v80, v27, v158
	v_fmac_f32_e32 v79, v27, v159
	v_fmac_f32_e32 v78, v27, v160
	v_fmac_f32_e32 v77, v27, v161
	ds_read_b128 v[158:161], v66 offset:12048
	s_waitcnt lgkmcnt(15)
	v_fmac_f32_e32 v76, v27, v162
	v_fmac_f32_e32 v75, v27, v163
	v_fmac_f32_e32 v74, v27, v164
	v_fmac_f32_e32 v73, v27, v165
	ds_read_b128 v[162:165], v66 offset:12064
	s_waitcnt lgkmcnt(15)
	v_fmac_f32_e32 v72, v27, v166
	v_fmac_f32_e32 v71, v27, v167
	v_fmac_f32_e32 v70, v27, v168
	v_fmac_f32_e32 v69, v27, v169
	ds_read_b128 v[166:169], v66 offset:12080
	s_waitcnt lgkmcnt(15)
	v_fmac_f32_e32 v84, v20, v102
	v_fmac_f32_e32 v83, v20, v103
	v_fmac_f32_e32 v82, v20, v104
	v_fmac_f32_e32 v81, v20, v105
	ds_read_b128 v[102:105], v66 offset:12288
	s_waitcnt lgkmcnt(15)
	v_fmac_f32_e32 v80, v20, v106
	v_fmac_f32_e32 v79, v20, v107
	v_fmac_f32_e32 v78, v20, v108
	v_fmac_f32_e32 v77, v20, v109
	ds_read_b128 v[106:109], v66 offset:12304
	s_waitcnt lgkmcnt(15)
	v_fmac_f32_e32 v76, v20, v110
	v_fmac_f32_e32 v75, v20, v111
	v_fmac_f32_e32 v74, v20, v112
	v_fmac_f32_e32 v73, v20, v113
	ds_read_b128 v[110:113], v66 offset:12320
	s_waitcnt lgkmcnt(15)
	v_fmac_f32_e32 v72, v20, v114
	v_fmac_f32_e32 v71, v20, v115
	v_fmac_f32_e32 v70, v20, v116
	v_fmac_f32_e32 v69, v20, v117
	ds_read_b128 v[114:117], v66 offset:12336
	s_waitcnt lgkmcnt(15)
	v_fmac_f32_e32 v84, v21, v118
	v_fmac_f32_e32 v83, v21, v119
	v_fmac_f32_e32 v82, v21, v120
	v_fmac_f32_e32 v81, v21, v121
	ds_read_b128 v[118:121], v66 offset:12544
	s_waitcnt lgkmcnt(15)
	v_fmac_f32_e32 v80, v21, v122
	v_fmac_f32_e32 v79, v21, v123
	v_fmac_f32_e32 v78, v21, v124
	v_fmac_f32_e32 v77, v21, v125
	ds_read_b128 v[122:125], v66 offset:12560
	s_waitcnt lgkmcnt(15)
	v_fmac_f32_e32 v76, v21, v126
	v_fmac_f32_e32 v75, v21, v127
	v_fmac_f32_e32 v74, v21, v128
	v_fmac_f32_e32 v73, v21, v129
	ds_read_b128 v[126:129], v66 offset:12576
	s_waitcnt lgkmcnt(15)
	v_fmac_f32_e32 v72, v21, v130
	v_fmac_f32_e32 v71, v21, v131
	v_fmac_f32_e32 v70, v21, v132
	v_fmac_f32_e32 v69, v21, v133
	ds_read_b128 v[130:133], v66 offset:12592
	s_waitcnt lgkmcnt(15)
	v_fmac_f32_e32 v84, v22, v134
	v_fmac_f32_e32 v83, v22, v135
	v_fmac_f32_e32 v82, v22, v136
	v_fmac_f32_e32 v81, v22, v137
	ds_read_b128 v[134:137], v66 offset:12800
	s_waitcnt lgkmcnt(15)
	v_fmac_f32_e32 v80, v22, v138
	v_fmac_f32_e32 v79, v22, v139
	v_fmac_f32_e32 v78, v22, v140
	v_fmac_f32_e32 v77, v22, v141
	ds_read_b128 v[138:141], v66 offset:12816
	s_waitcnt lgkmcnt(15)
	v_fmac_f32_e32 v76, v22, v142
	v_fmac_f32_e32 v75, v22, v143
	v_fmac_f32_e32 v74, v22, v144
	v_fmac_f32_e32 v73, v22, v145
	ds_read_b128 v[142:145], v66 offset:12832
	s_waitcnt lgkmcnt(15)
; #define LAS __attribute__((address_space(3)))
; __device__ __forceinline__ void phase_prep(const Params& p, LAS unsigned char* lds) {
;     ...
;             for (int c4 = 0; c4 < 16; ++c4)
; #pragma unroll
;                 for (int cc = 0; cc < 4; ++cc) { const float wv = rw[c4][cc]; const LAS f32x4* mp = (const LAS f32x4*)(Mf + (4 * c4 + cc) * 64 + eg * 16);
; #pragma unroll
;                     for (int j4 = 0; j4 < 4; ++j4) { const f32x4 mv = mp[j4]; a[4 * j4 + 0] += wv * mv[0]; a[4 * j4 + 1] += wv * mv[1]; a[4 * j4 + 2] += wv * mv[2]; a[4 * j4 + 3] += wv * mv[3]; } }
	v_fmac_f32_e32 v72, v22, v146
	v_fmac_f32_e32 v71, v22, v147
	v_fmac_f32_e32 v70, v22, v148
	v_fmac_f32_e32 v69, v22, v149
	ds_read_b128 v[146:149], v66 offset:12848
	s_waitcnt lgkmcnt(15)
	v_fmac_f32_e32 v84, v23, v150
	v_fmac_f32_e32 v83, v23, v151
	v_fmac_f32_e32 v82, v23, v152
	v_fmac_f32_e32 v81, v23, v153
	ds_read_b128 v[150:153], v66 offset:13056
	s_waitcnt lgkmcnt(15)
	v_fmac_f32_e32 v80, v23, v158
	v_fmac_f32_e32 v79, v23, v159
	v_fmac_f32_e32 v78, v23, v160
	v_fmac_f32_e32 v77, v23, v161
	ds_read_b128 v[158:161], v66 offset:13072
	s_waitcnt lgkmcnt(15)
	v_fmac_f32_e32 v76, v23, v162
	v_fmac_f32_e32 v75, v23, v163
	v_fmac_f32_e32 v74, v23, v164
	v_fmac_f32_e32 v73, v23, v165
	ds_read_b128 v[162:165], v66 offset:13088
	s_waitcnt lgkmcnt(15)
	v_fmac_f32_e32 v72, v23, v166
	v_fmac_f32_e32 v71, v23, v167
	v_fmac_f32_e32 v70, v23, v168
	v_fmac_f32_e32 v69, v23, v169
	ds_read_b128 v[166:169], v66 offset:13104
	s_waitcnt lgkmcnt(15)
	v_fmac_f32_e32 v84, v16, v102
	v_fmac_f32_e32 v83, v16, v103
	v_fmac_f32_e32 v82, v16, v104
	v_fmac_f32_e32 v81, v16, v105
	ds_read_b128 v[102:105], v66 offset:13312
	s_waitcnt lgkmcnt(15)
	v_fmac_f32_e32 v80, v16, v106
	v_fmac_f32_e32 v79, v16, v107
	v_fmac_f32_e32 v78, v16, v108
	v_fmac_f32_e32 v77, v16, v109
	ds_read_b128 v[106:109], v66 offset:13328
	s_waitcnt lgkmcnt(15)
	v_fmac_f32_e32 v76, v16, v110
	v_fmac_f32_e32 v75, v16, v111
	v_fmac_f32_e32 v74, v16, v112
	v_fmac_f32_e32 v73, v16, v113
	ds_read_b128 v[110:113], v66 offset:13344
	s_waitcnt lgkmcnt(15)
	v_fmac_f32_e32 v72, v16, v114
	v_fmac_f32_e32 v71, v16, v115
	v_fmac_f32_e32 v70, v16, v116
	v_fmac_f32_e32 v69, v16, v117
	ds_read_b128 v[114:117], v66 offset:13360
	s_waitcnt lgkmcnt(15)
	v_fmac_f32_e32 v84, v17, v118
	v_fmac_f32_e32 v83, v17, v119
	v_fmac_f32_e32 v82, v17, v120
	v_fmac_f32_e32 v81, v17, v121
	ds_read_b128 v[118:121], v66 offset:13568
	s_waitcnt lgkmcnt(15)
	v_fmac_f32_e32 v80, v17, v122
	v_fmac_f32_e32 v79, v17, v123
	v_fmac_f32_e32 v78, v17, v124
	v_fmac_f32_e32 v77, v17, v125
	ds_read_b128 v[122:125], v66 offset:13584
	s_waitcnt lgkmcnt(15)
	v_fmac_f32_e32 v76, v17, v126
	v_fmac_f32_e32 v75, v17, v127
	v_fmac_f32_e32 v74, v17, v128
	v_fmac_f32_e32 v73, v17, v129
	ds_read_b128 v[126:129], v66 offset:13600
	s_waitcnt lgkmcnt(15)
	v_fmac_f32_e32 v72, v17, v130
	v_fmac_f32_e32 v71, v17, v131
	v_fmac_f32_e32 v70, v17, v132
	v_fmac_f32_e32 v69, v17, v133
	ds_read_b128 v[130:133], v66 offset:13616
	s_waitcnt lgkmcnt(15)
	v_fmac_f32_e32 v84, v18, v134
	v_fmac_f32_e32 v83, v18, v135
	v_fmac_f32_e32 v82, v18, v136
	v_fmac_f32_e32 v81, v18, v137
	ds_read_b128 v[134:137], v66 offset:13824
	s_waitcnt lgkmcnt(15)
	v_fmac_f32_e32 v80, v18, v138
	v_fmac_f32_e32 v79, v18, v139
	v_fmac_f32_e32 v78, v18, v140
	v_fmac_f32_e32 v77, v18, v141
	ds_read_b128 v[138:141], v66 offset:13840
	s_waitcnt lgkmcnt(15)
	v_fmac_f32_e32 v76, v18, v142
	v_fmac_f32_e32 v75, v18, v143
	v_fmac_f32_e32 v74, v18, v144
	v_fmac_f32_e32 v73, v18, v145
	ds_read_b128 v[142:145], v66 offset:13856
	s_waitcnt lgkmcnt(15)
	v_fmac_f32_e32 v72, v18, v146
	v_fmac_f32_e32 v71, v18, v147
	v_fmac_f32_e32 v70, v18, v148
	v_fmac_f32_e32 v69, v18, v149
	ds_read_b128 v[146:149], v66 offset:13872
	s_waitcnt lgkmcnt(15)
	v_fmac_f32_e32 v84, v19, v150
	v_fmac_f32_e32 v83, v19, v151
	v_fmac_f32_e32 v82, v19, v152
	v_fmac_f32_e32 v81, v19, v153
	ds_read_b128 v[150:153], v66 offset:14080
	s_waitcnt lgkmcnt(15)
	v_fmac_f32_e32 v80, v19, v158
	v_fmac_f32_e32 v79, v19, v159
	v_fmac_f32_e32 v78, v19, v160
	v_fmac_f32_e32 v77, v19, v161
	ds_read_b128 v[158:161], v66 offset:14096
	s_waitcnt lgkmcnt(15)
	v_fmac_f32_e32 v76, v19, v162
	v_fmac_f32_e32 v75, v19, v163
	v_fmac_f32_e32 v74, v19, v164
	v_fmac_f32_e32 v73, v19, v165
	ds_read_b128 v[162:165], v66 offset:14112
	s_waitcnt lgkmcnt(15)
	v_fmac_f32_e32 v72, v19, v166
	v_fmac_f32_e32 v71, v19, v167
	v_fmac_f32_e32 v70, v19, v168
	v_fmac_f32_e32 v69, v19, v169
	ds_read_b128 v[166:169], v66 offset:14128
	s_waitcnt lgkmcnt(15)
	v_fmac_f32_e32 v84, v12, v102
	v_fmac_f32_e32 v83, v12, v103
	v_fmac_f32_e32 v82, v12, v104
	v_fmac_f32_e32 v81, v12, v105
	ds_read_b128 v[102:105], v66 offset:14336
	s_waitcnt lgkmcnt(15)
	v_fmac_f32_e32 v80, v12, v106
	v_fmac_f32_e32 v79, v12, v107
	v_fmac_f32_e32 v78, v12, v108
	v_fmac_f32_e32 v77, v12, v109
	ds_read_b128 v[106:109], v66 offset:14352
	s_waitcnt lgkmcnt(15)
	v_fmac_f32_e32 v76, v12, v110
	v_fmac_f32_e32 v75, v12, v111
	v_fmac_f32_e32 v74, v12, v112
	v_fmac_f32_e32 v73, v12, v113
	ds_read_b128 v[110:113], v66 offset:14368
	s_waitcnt lgkmcnt(15)
	v_fmac_f32_e32 v72, v12, v114
	v_fmac_f32_e32 v71, v12, v115
	v_fmac_f32_e32 v70, v12, v116
	v_fmac_f32_e32 v69, v12, v117
	ds_read_b128 v[114:117], v66 offset:14384
	s_waitcnt lgkmcnt(15)
	v_fmac_f32_e32 v84, v13, v118
	v_fmac_f32_e32 v83, v13, v119
	v_fmac_f32_e32 v82, v13, v120
	v_fmac_f32_e32 v81, v13, v121
	ds_read_b128 v[118:121], v66 offset:14592
	s_waitcnt lgkmcnt(15)
	v_fmac_f32_e32 v80, v13, v122
	v_fmac_f32_e32 v79, v13, v123
	v_fmac_f32_e32 v78, v13, v124
	v_fmac_f32_e32 v77, v13, v125
	ds_read_b128 v[122:125], v66 offset:14608
	s_waitcnt lgkmcnt(15)
	v_fmac_f32_e32 v76, v13, v126
	v_fmac_f32_e32 v75, v13, v127
	v_fmac_f32_e32 v74, v13, v128
	v_fmac_f32_e32 v73, v13, v129
	ds_read_b128 v[126:129], v66 offset:14624
	s_waitcnt lgkmcnt(15)
	v_fmac_f32_e32 v72, v13, v130
	v_fmac_f32_e32 v71, v13, v131
	v_fmac_f32_e32 v70, v13, v132
	v_fmac_f32_e32 v69, v13, v133
	ds_read_b128 v[130:133], v66 offset:14640
	s_waitcnt lgkmcnt(15)
	v_fmac_f32_e32 v84, v14, v134
	v_fmac_f32_e32 v83, v14, v135
	v_fmac_f32_e32 v82, v14, v136
	v_fmac_f32_e32 v81, v14, v137
	ds_read_b128 v[134:137], v66 offset:14848
	s_waitcnt lgkmcnt(15)
; #define LAS __attribute__((address_space(3)))
; __device__ __forceinline__ void phase_prep(const Params& p, LAS unsigned char* lds) {
;     ...
;             for (int c4 = 0; c4 < 16; ++c4)
; #pragma unroll
;                 for (int cc = 0; cc < 4; ++cc) { const float wv = rw[c4][cc]; const LAS f32x4* mp = (const LAS f32x4*)(Mf + (4 * c4 + cc) * 64 + eg * 16);
; #pragma unroll
;                     for (int j4 = 0; j4 < 4; ++j4) { const f32x4 mv = mp[j4]; a[4 * j4 + 0] += wv * mv[0]; a[4 * j4 + 1] += wv * mv[1]; a[4 * j4 + 2] += wv * mv[2]; a[4 * j4 + 3] += wv * mv[3]; } }
	v_fmac_f32_e32 v80, v14, v138
	v_fmac_f32_e32 v79, v14, v139
	v_fmac_f32_e32 v78, v14, v140
	v_fmac_f32_e32 v77, v14, v141
	ds_read_b128 v[138:141], v66 offset:14864
	s_waitcnt lgkmcnt(15)
	v_fmac_f32_e32 v76, v14, v142
	v_fmac_f32_e32 v75, v14, v143
	v_fmac_f32_e32 v74, v14, v144
	v_fmac_f32_e32 v73, v14, v145
	ds_read_b128 v[142:145], v66 offset:14880
	s_waitcnt lgkmcnt(15)
	v_fmac_f32_e32 v72, v14, v146
	v_fmac_f32_e32 v71, v14, v147
	v_fmac_f32_e32 v70, v14, v148
	v_fmac_f32_e32 v69, v14, v149
	ds_read_b128 v[146:149], v66 offset:14896
	s_waitcnt lgkmcnt(15)
	v_fmac_f32_e32 v84, v15, v150
	v_fmac_f32_e32 v83, v15, v151
	v_fmac_f32_e32 v82, v15, v152
	v_fmac_f32_e32 v81, v15, v153
	ds_read_b128 v[150:153], v66 offset:15104
	s_waitcnt lgkmcnt(15)
	v_fmac_f32_e32 v80, v15, v158
	v_fmac_f32_e32 v79, v15, v159
	v_fmac_f32_e32 v78, v15, v160
	v_fmac_f32_e32 v77, v15, v161
	ds_read_b128 v[158:161], v66 offset:15120
	s_waitcnt lgkmcnt(15)
	v_fmac_f32_e32 v76, v15, v162
	v_fmac_f32_e32 v75, v15, v163
	v_fmac_f32_e32 v74, v15, v164
	v_fmac_f32_e32 v73, v15, v165
	ds_read_b128 v[162:165], v66 offset:15136
	s_waitcnt lgkmcnt(15)
	v_fmac_f32_e32 v72, v15, v166
	v_fmac_f32_e32 v71, v15, v167
	v_fmac_f32_e32 v70, v15, v168
	v_fmac_f32_e32 v69, v15, v169
	ds_read_b128 v[166:169], v66 offset:15152
	s_waitcnt lgkmcnt(15)
	v_fmac_f32_e32 v84, v8, v102
	v_fmac_f32_e32 v83, v8, v103
	v_fmac_f32_e32 v82, v8, v104
	v_fmac_f32_e32 v81, v8, v105
	ds_read_b128 v[102:105], v66 offset:15360
	s_waitcnt lgkmcnt(15)
	v_fmac_f32_e32 v80, v8, v106
	v_fmac_f32_e32 v79, v8, v107
	v_fmac_f32_e32 v78, v8, v108
	v_fmac_f32_e32 v77, v8, v109
	ds_read_b128 v[106:109], v66 offset:15376
	s_waitcnt lgkmcnt(15)
	v_fmac_f32_e32 v76, v8, v110
	v_fmac_f32_e32 v75, v8, v111
	v_fmac_f32_e32 v74, v8, v112
	v_fmac_f32_e32 v73, v8, v113
	ds_read_b128 v[110:113], v66 offset:15392
	s_waitcnt lgkmcnt(15)
	v_fmac_f32_e32 v72, v8, v114
	v_fmac_f32_e32 v71, v8, v115
	v_fmac_f32_e32 v70, v8, v116
	v_fmac_f32_e32 v69, v8, v117
	ds_read_b128 v[114:117], v66 offset:15408
	s_waitcnt lgkmcnt(15)
	v_fmac_f32_e32 v84, v9, v118
	v_fmac_f32_e32 v83, v9, v119
	v_fmac_f32_e32 v82, v9, v120
	v_fmac_f32_e32 v81, v9, v121
	ds_read_b128 v[118:121], v66 offset:15616
	s_waitcnt lgkmcnt(15)
	v_fmac_f32_e32 v80, v9, v122
	v_fmac_f32_e32 v79, v9, v123
	v_fmac_f32_e32 v78, v9, v124
	v_fmac_f32_e32 v77, v9, v125
	ds_read_b128 v[122:125], v66 offset:15632
	s_waitcnt lgkmcnt(15)
	v_fmac_f32_e32 v76, v9, v126
	v_fmac_f32_e32 v75, v9, v127
	v_fmac_f32_e32 v74, v9, v128
	v_fmac_f32_e32 v73, v9, v129
	ds_read_b128 v[126:129], v66 offset:15648
	s_waitcnt lgkmcnt(15)
	v_fmac_f32_e32 v72, v9, v130
	v_fmac_f32_e32 v71, v9, v131
	v_fmac_f32_e32 v70, v9, v132
	v_fmac_f32_e32 v69, v9, v133
	ds_read_b128 v[130:133], v66 offset:15664
	s_waitcnt lgkmcnt(15)
	v_fmac_f32_e32 v84, v10, v134
	v_fmac_f32_e32 v83, v10, v135
	v_fmac_f32_e32 v82, v10, v136
	v_fmac_f32_e32 v81, v10, v137
	ds_read_b128 v[134:137], v66 offset:15872
	s_waitcnt lgkmcnt(15)
	v_fmac_f32_e32 v80, v10, v138
	v_fmac_f32_e32 v79, v10, v139
	v_fmac_f32_e32 v78, v10, v140
	v_fmac_f32_e32 v77, v10, v141
	ds_read_b128 v[138:141], v66 offset:15888
	s_waitcnt lgkmcnt(15)
	v_fmac_f32_e32 v76, v10, v142
	v_fmac_f32_e32 v75, v10, v143
	v_fmac_f32_e32 v74, v10, v144
	v_fmac_f32_e32 v73, v10, v145
	ds_read_b128 v[142:145], v66 offset:15904
	s_waitcnt lgkmcnt(15)
	v_fmac_f32_e32 v72, v10, v146
	v_fmac_f32_e32 v71, v10, v147
	v_fmac_f32_e32 v70, v10, v148
	v_fmac_f32_e32 v69, v10, v149
	ds_read_b128 v[146:149], v66 offset:15920
	s_waitcnt lgkmcnt(15)
	v_fmac_f32_e32 v84, v11, v150
	v_fmac_f32_e32 v83, v11, v151
	v_fmac_f32_e32 v82, v11, v152
	v_fmac_f32_e32 v81, v11, v153
	ds_read_b128 v[150:153], v66 offset:16128
	s_waitcnt lgkmcnt(15)
	v_fmac_f32_e32 v80, v11, v158
	v_fmac_f32_e32 v79, v11, v159
	v_fmac_f32_e32 v78, v11, v160
	v_fmac_f32_e32 v77, v11, v161
	ds_read_b128 v[158:161], v66 offset:16144
	s_waitcnt lgkmcnt(15)
	v_fmac_f32_e32 v76, v11, v162
	v_fmac_f32_e32 v75, v11, v163
	v_fmac_f32_e32 v74, v11, v164
	v_fmac_f32_e32 v73, v11, v165
	ds_read_b128 v[162:165], v66 offset:16160
	s_waitcnt lgkmcnt(15)
	v_fmac_f32_e32 v72, v11, v166
	v_fmac_f32_e32 v71, v11, v167
	v_fmac_f32_e32 v70, v11, v168
	v_fmac_f32_e32 v69, v11, v169
	ds_read_b128 v[166:169], v66 offset:16176
	s_waitcnt lgkmcnt(15)
	v_fmac_f32_e32 v84, v4, v102
	v_fmac_f32_e32 v83, v4, v103
	v_fmac_f32_e32 v82, v4, v104
	v_fmac_f32_e32 v81, v4, v105
	ds_read_b128 v[102:105], v66 offset:16384
	s_waitcnt lgkmcnt(15)
	v_fmac_f32_e32 v80, v4, v106
	v_fmac_f32_e32 v79, v4, v107
	v_fmac_f32_e32 v78, v4, v108
	v_fmac_f32_e32 v77, v4, v109
	ds_read_b128 v[106:109], v66 offset:16400
	s_waitcnt lgkmcnt(15)
	v_fmac_f32_e32 v76, v4, v110
	v_fmac_f32_e32 v75, v4, v111
	v_fmac_f32_e32 v74, v4, v112
	v_fmac_f32_e32 v73, v4, v113
	ds_read_b128 v[110:113], v66 offset:16416
	s_waitcnt lgkmcnt(15)
	v_fmac_f32_e32 v72, v4, v114
	v_fmac_f32_e32 v71, v4, v115
	v_fmac_f32_e32 v70, v4, v116
	v_fmac_f32_e32 v69, v4, v117
	ds_read_b128 v[114:117], v66 offset:16432
	s_waitcnt lgkmcnt(15)
	v_fmac_f32_e32 v84, v5, v118
	v_fmac_f32_e32 v83, v5, v119
	v_fmac_f32_e32 v82, v5, v120
	v_fmac_f32_e32 v81, v5, v121
	ds_read_b128 v[118:121], v66 offset:16640
	s_waitcnt lgkmcnt(15)
	v_fmac_f32_e32 v80, v5, v122
	v_fmac_f32_e32 v79, v5, v123
	v_fmac_f32_e32 v78, v5, v124
	v_fmac_f32_e32 v77, v5, v125
	ds_read_b128 v[122:125], v66 offset:16656
	s_waitcnt lgkmcnt(15)
	v_fmac_f32_e32 v76, v5, v126
	v_fmac_f32_e32 v75, v5, v127
	v_fmac_f32_e32 v74, v5, v128
	v_fmac_f32_e32 v73, v5, v129
	ds_read_b128 v[126:129], v66 offset:16672
	s_waitcnt lgkmcnt(15)
; #define LAS __attribute__((address_space(3)))
; __device__ __forceinline__ unsigned f2bf(float f) { unsigned u = __builtin_bit_cast(unsigned, f); return (u + 0x7fffu + ((u >> 16) & 1u)) >> 16; }
; __device__ __forceinline__ void phase_prep(const Params& p, LAS unsigned char* lds) {
;     ...
;             for (int c4 = 0; c4 < 16; ++c4)
; #pragma unroll
;                 for (int cc = 0; cc < 4; ++cc) { const float wv = rw[c4][cc]; const LAS f32x4* mp = (const LAS f32x4*)(Mf + (4 * c4 + cc) * 64 + eg * 16);
; #pragma unroll
;                     for (int j4 = 0; j4 < 4; ++j4) { const f32x4 mv = mp[j4]; a[4 * j4 + 0] += wv * mv[0]; a[4 * j4 + 1] += wv * mv[1]; a[4 * j4 + 2] += wv * mv[2]; a[4 * j4 + 3] += wv * mv[3]; } }
;             bf16_t* wt = (bf16_t*)(ws + WS_WF + l * SZ_WF);
; #pragma unroll
;             for (int j = 0; j < 16; ++j) wt[(size_t)(part * 512 + g * 64 + eg * 16 + j) * DM + k] = (bf16_t)f2bf(a[j]);
;             }
	v_fmac_f32_e32 v72, v5, v130
	v_fmac_f32_e32 v71, v5, v131
	v_fmac_f32_e32 v70, v5, v132
	v_fmac_f32_e32 v69, v5, v133
	ds_read_b128 v[130:133], v66 offset:16688
	s_waitcnt lgkmcnt(15)
	v_fmac_f32_e32 v84, v6, v134
	v_fmac_f32_e32 v83, v6, v135
	v_fmac_f32_e32 v82, v6, v136
	v_fmac_f32_e32 v81, v6, v137
	ds_read_b128 v[134:137], v66 offset:16896
	s_waitcnt lgkmcnt(15)
	v_fmac_f32_e32 v80, v6, v138
	v_fmac_f32_e32 v79, v6, v139
	v_fmac_f32_e32 v78, v6, v140
	v_fmac_f32_e32 v77, v6, v141
	ds_read_b128 v[138:141], v66 offset:16912
	s_waitcnt lgkmcnt(15)
	v_fmac_f32_e32 v76, v6, v142
	v_fmac_f32_e32 v75, v6, v143
	v_fmac_f32_e32 v74, v6, v144
	v_fmac_f32_e32 v73, v6, v145
	ds_read_b128 v[142:145], v66 offset:16928
	s_waitcnt lgkmcnt(15)
	v_fmac_f32_e32 v72, v6, v146
	v_fmac_f32_e32 v71, v6, v147
	v_fmac_f32_e32 v70, v6, v148
	v_fmac_f32_e32 v69, v6, v149
	ds_read_b128 v[146:149], v66 offset:16944
	s_waitcnt lgkmcnt(15)
	v_fmac_f32_e32 v84, v7, v150
	v_fmac_f32_e32 v83, v7, v151
	v_fmac_f32_e32 v82, v7, v152
	v_fmac_f32_e32 v81, v7, v153
	ds_read_b128 v[150:153], v66 offset:17152
	s_waitcnt lgkmcnt(15)
	v_fmac_f32_e32 v80, v7, v158
	v_fmac_f32_e32 v79, v7, v159
	v_fmac_f32_e32 v78, v7, v160
	v_fmac_f32_e32 v77, v7, v161
	ds_read_b128 v[158:161], v66 offset:17168
	s_waitcnt lgkmcnt(15)
	v_fmac_f32_e32 v76, v7, v162
	v_fmac_f32_e32 v75, v7, v163
	v_fmac_f32_e32 v74, v7, v164
	v_fmac_f32_e32 v73, v7, v165
	ds_read_b128 v[162:165], v66 offset:17184
	s_waitcnt lgkmcnt(15)
	v_fmac_f32_e32 v72, v7, v166
	v_fmac_f32_e32 v71, v7, v167
	v_fmac_f32_e32 v70, v7, v168
	v_fmac_f32_e32 v69, v7, v169
	ds_read_b128 v[166:169], v66 offset:17200
	s_waitcnt lgkmcnt(15)
	v_fmac_f32_e32 v84, v0, v102
	v_fmac_f32_e32 v83, v0, v103
	v_fmac_f32_e32 v82, v0, v104
	v_fmac_f32_e32 v81, v0, v105
	s_waitcnt lgkmcnt(14)
	v_fmac_f32_e32 v80, v0, v106
	v_fmac_f32_e32 v79, v0, v107
	v_fmac_f32_e32 v78, v0, v108
	v_fmac_f32_e32 v77, v0, v109
	s_waitcnt lgkmcnt(13)
	v_fmac_f32_e32 v76, v0, v110
	v_fmac_f32_e32 v75, v0, v111
	v_fmac_f32_e32 v74, v0, v112
	v_fmac_f32_e32 v73, v0, v113
	s_waitcnt lgkmcnt(12)
	v_fmac_f32_e32 v72, v0, v114
	v_fmac_f32_e32 v71, v0, v115
	v_fmac_f32_e32 v70, v0, v116
	v_fmac_f32_e32 v69, v0, v117
	s_waitcnt lgkmcnt(11)
	v_fmac_f32_e32 v84, v1, v118
	v_fmac_f32_e32 v83, v1, v119
	v_fmac_f32_e32 v82, v1, v120
	v_fmac_f32_e32 v81, v1, v121
	s_waitcnt lgkmcnt(10)
	v_fmac_f32_e32 v80, v1, v122
	v_fmac_f32_e32 v79, v1, v123
	v_fmac_f32_e32 v78, v1, v124
	v_fmac_f32_e32 v77, v1, v125
	s_waitcnt lgkmcnt(9)
	v_fmac_f32_e32 v76, v1, v126
	v_fmac_f32_e32 v75, v1, v127
	v_fmac_f32_e32 v74, v1, v128
	v_fmac_f32_e32 v73, v1, v129
	s_waitcnt lgkmcnt(8)
	v_fmac_f32_e32 v72, v1, v130
	v_fmac_f32_e32 v71, v1, v131
	v_fmac_f32_e32 v70, v1, v132
	v_fmac_f32_e32 v69, v1, v133
	s_waitcnt lgkmcnt(7)
	v_fmac_f32_e32 v84, v2, v134
	v_fmac_f32_e32 v83, v2, v135
	v_fmac_f32_e32 v82, v2, v136
	v_fmac_f32_e32 v81, v2, v137
	s_waitcnt lgkmcnt(6)
	v_fmac_f32_e32 v80, v2, v138
	v_fmac_f32_e32 v79, v2, v139
	v_fmac_f32_e32 v78, v2, v140
	v_fmac_f32_e32 v77, v2, v141
	s_waitcnt lgkmcnt(5)
	v_fmac_f32_e32 v76, v2, v142
	v_fmac_f32_e32 v75, v2, v143
	v_fmac_f32_e32 v74, v2, v144
	v_fmac_f32_e32 v73, v2, v145
	s_waitcnt lgkmcnt(4)
	v_fmac_f32_e32 v72, v2, v146
	v_fmac_f32_e32 v71, v2, v147
	v_fmac_f32_e32 v70, v2, v148
	v_fmac_f32_e32 v69, v2, v149
	s_waitcnt lgkmcnt(3)
	v_fmac_f32_e32 v84, v3, v150
	v_fmac_f32_e32 v83, v3, v151
	v_fmac_f32_e32 v82, v3, v152
	v_fmac_f32_e32 v81, v3, v153
	s_waitcnt lgkmcnt(2)
	v_fmac_f32_e32 v80, v3, v158
	v_fmac_f32_e32 v79, v3, v159
	v_fmac_f32_e32 v78, v3, v160
	v_fmac_f32_e32 v77, v3, v161
	s_waitcnt lgkmcnt(1)
	v_fmac_f32_e32 v76, v3, v162
	v_fmac_f32_e32 v75, v3, v163
	v_fmac_f32_e32 v74, v3, v164
	v_fmac_f32_e32 v73, v3, v165
	s_waitcnt lgkmcnt(0)
	v_fmac_f32_e32 v72, v3, v166
	v_fmac_f32_e32 v71, v3, v167
	v_fmac_f32_e32 v70, v3, v168
	v_fmac_f32_e32 v69, v3, v169
	v_bfe_u32 v0, v84, 16, 1
	v_add3_u32 v0, v84, v0, s34
	v_lshl_add_u64 v[2:3], v[60:61], 0, s[0:1]
	v_add_co_u32_e32 v4, vcc, s2, v2
	s_mov_b32 s2, 0x4003000
	s_nop 0
	v_addc_co_u32_e32 v5, vcc, 0, v3, vcc
	global_store_short_d16_hi v[4:5], v0, off offset:-4096
	v_bfe_u32 v0, v83, 16, 1
	v_add3_u32 v0, v83, v0, s34
	global_store_short_d16_hi v[4:5], v0, off
	v_bfe_u32 v0, v82, 16, 1
	v_add3_u32 v4, v82, v0, s34
	v_add_co_u32_e32 v0, vcc, s2, v2
	s_mov_b32 s2, 0x4005000
	s_nop 0
	v_addc_co_u32_e32 v1, vcc, 0, v3, vcc
	global_store_short_d16_hi v[0:1], v4, off offset:-4096
	v_bfe_u32 v4, v81, 16, 1
	v_add3_u32 v4, v81, v4, s34
	global_store_short_d16_hi v[0:1], v4, off
	v_bfe_u32 v0, v80, 16, 1
	v_add3_u32 v4, v80, v0, s34
	v_add_co_u32_e32 v0, vcc, s2, v2
	s_mov_b32 s2, 0x4007000
	s_nop 0
	v_addc_co_u32_e32 v1, vcc, 0, v3, vcc
	global_store_short_d16_hi v[0:1], v4, off offset:-4096
	v_bfe_u32 v4, v79, 16, 1
	v_add3_u32 v4, v79, v4, s34
	global_store_short_d16_hi v[0:1], v4, off
	v_bfe_u32 v0, v78, 16, 1
	v_add3_u32 v4, v78, v0, s34
	v_add_co_u32_e32 v0, vcc, s2, v2
	s_mov_b32 s2, 0x4009000
	s_nop 0
	v_addc_co_u32_e32 v1, vcc, 0, v3, vcc
	global_store_short_d16_hi v[0:1], v4, off offset:-4096
	v_bfe_u32 v4, v77, 16, 1
	v_add3_u32 v4, v77, v4, s34
	global_store_short_d16_hi v[0:1], v4, off
	v_bfe_u32 v0, v76, 16, 1
	v_add3_u32 v4, v76, v0, s34
	v_add_co_u32_e32 v0, vcc, s2, v2
	s_mov_b32 s2, 0x400b000
	s_nop 0
	v_addc_co_u32_e32 v1, vcc, 0, v3, vcc
	global_store_short_d16_hi v[0:1], v4, off offset:-4096
	v_bfe_u32 v4, v75, 16, 1
	v_add3_u32 v4, v75, v4, s34
	global_store_short_d16_hi v[0:1], v4, off
	v_bfe_u32 v0, v74, 16, 1
	v_add3_u32 v4, v74, v0, s34
	v_add_co_u32_e32 v0, vcc, s2, v2
	s_mov_b32 s2, 0x400d000
	s_nop 0
	v_addc_co_u32_e32 v1, vcc, 0, v3, vcc
	global_store_short_d16_hi v[0:1], v4, off offset:-4096
	v_bfe_u32 v4, v73, 16, 1
	v_add3_u32 v4, v73, v4, s34
	global_store_short_d16_hi v[0:1], v4, off
	v_bfe_u32 v0, v72, 16, 1
	v_add3_u32 v4, v72, v0, s34
	v_add_co_u32_e32 v0, vcc, s2, v2
	s_mov_b32 s2, 0x400e000
	s_nop 0
	v_addc_co_u32_e32 v1, vcc, 0, v3, vcc
	global_store_short_d16_hi v[0:1], v4, off offset:-4096
	v_bfe_u32 v4, v71, 16, 1
	v_add3_u32 v4, v71, v4, s34
	global_store_short_d16_hi v[0:1], v4, off
	v_bfe_u32 v0, v70, 16, 1
	v_add3_u32 v4, v70, v0, s34
	v_add_co_u32_e32 v0, vcc, s2, v2
	s_add_u32 s0, s0, 0x100
	s_nop 0
	v_addc_co_u32_e32 v1, vcc, 0, v3, vcc
	global_store_short_d16_hi v[0:1], v4, off
	v_bfe_u32 v0, v69, 16, 1
	v_add3_u32 v4, v69, v0, s34
	v_add_co_u32_e32 v0, vcc, 0x400f000, v2
	s_addc_u32 s1, s1, 0
	s_mov_b64 s[2:3], 0x240000
	v_addc_co_u32_e32 v1, vcc, 0, v3, vcc
	v_lshl_add_u64 v[62:63], v[62:63], 0, s[2:3]
	s_cmpk_eq_i32 s0, 0x400
	global_store_short_d16_hi v[0:1], v4, off
	s_cbranch_scc0 .LBB0_581
	s_add_i32 s10, s10, s15
	s_add_i32 s8, s8, s9
	s_cmpk_gt_i32 s10, 0xff
	s_cbranch_scc0 .LBB0_575
